# B1 barrier + peeled C=0 first iteration + SwiGLU epilogue scalar mul/add pairs packed (v_pk_mul_f32 / v_pk_add_f32)
# baseline (speedup 1.0000x reference)
_Z10fwd_kernel4Args:
	s_load_dword s90, s[0:1], 0xf8
	s_mov_b32 s98, 0xbfb8aa3b
	s_mov_b32 s99, 0xbfb8aa3b
	s_mov_b32 s100, 1.0
	s_mov_b32 s101, 1.0
	v_writelane_b32 v249, s2, 0
	s_add_u32 s2, s0, 0xf8
	s_addc_u32 s3, s1, 0
	v_writelane_b32 v249, s2, 1
	v_mov_b32_e32 v2, 0
	v_or_b32_e32 v195, 0x400, v0
	v_writelane_b32 v249, s3, 2
	s_add_i32 s2, 0, 0x20000
	v_lshl_add_u32 v1, v0, 2, s2
	ds_write2st64_b32 v1, v2, v2 offset1:8
	v_lshl_add_u32 v1, v195, 2, s2
	v_readfirstlane_b32 s88, v0
	ds_write2st64_b32 v1, v2, v2 offset1:8
	v_or_b32_e32 v1, 0x800, v0
	s_mov_b64 s[4:5], -1
	s_and_saveexec_b64 s[6:7], s[4:5]
	v_lshl_add_u32 v3, v1, 2, 0
	v_add_u32_e32 v3, 0x20000, v3
	ds_write_b32 v3, v2
	s_or_b64 exec, exec, s[6:7]
	s_load_dwordx4 s[80:83], s[0:1], 0xe0
	s_load_dwordx8 s[8:15], s[0:1], 0xc0
	s_waitcnt lgkmcnt(0)
	v_writelane_b32 v249, s8, 3
	s_nop 1
	v_writelane_b32 v249, s9, 4
	v_writelane_b32 v249, s10, 5
	v_writelane_b32 v249, s11, 6
	v_writelane_b32 v249, s12, 7
	v_writelane_b32 v249, s13, 8
	v_writelane_b32 v249, s14, 9
	v_writelane_b32 v249, s15, 10
	s_and_saveexec_b64 s[6:7], s[4:5]
	v_lshl_add_u32 v2, v1, 2, s2
	v_mov_b32_e32 v3, 0
	ds_write_b32 v2, v3 offset:2048
	s_or_b64 exec, exec, s[6:7]
	s_load_dwordx2 s[4:5], s[0:1], 0xf0
	v_or_b32_e32 v2, 0xc00, v0
	v_cmp_gt_u32_e64 s[8:9], 7, 5
	s_waitcnt lgkmcnt(0)
	v_writelane_b32 v249, s4, 11
	s_nop 1
	v_writelane_b32 v249, s5, 12
	v_cmp_gt_u32_e64 s[4:5], 7, 6
	s_and_saveexec_b64 s[6:7], s[8:9]
	v_readlane_b32 s3, v249, 0
	v_lshl_add_u32 v3, v2, 2, 0
	v_add_u32_e32 v3, 0x20000, v3
	v_mov_b32_e32 v4, 0
	ds_write_b32 v3, v4
	s_or_b64 exec, exec, s[6:7]
	s_and_saveexec_b64 s[6:7], s[4:5]
	v_lshl_add_u32 v2, v2, 2, s2
	v_mov_b32_e32 v3, 0
	ds_write_b32 v2, v3 offset:2048
	s_or_b64 exec, exec, s[6:7]
	s_load_dwordx2 s[4:5], s[0:1], 0xf0
	s_mov_b32 s86, 0
	v_cmp_eq_u32_e32 vcc, 0, v0
	s_mov_b32 s87, 0
	s_waitcnt lgkmcnt(0)
	s_sub_i32 s2, s5, s4
	s_add_u32 s84, s82, 0x4000
	s_addc_u32 s85, s83, 0
	s_cmp_lt_i32 s2, 2
	s_barrier
	s_cbranch_scc1 .LBB0_13
	s_getreg_b32 s2, hwreg(HW_REG_XCC_ID, 0, 4)
	s_and_b32 s86, s2, 15
	s_and_saveexec_b64 s[4:5], vcc
	s_cbranch_execz .LBB0_12
	s_mov_b64 s[6:7], exec
	v_mbcnt_lo_u32_b32 v2, s6, 0
	v_mbcnt_hi_u32_b32 v2, s7, v2
	v_cmp_eq_u32_e32 vcc, 0, v2
	s_and_b64 s[2:3], exec, vcc
	s_mov_b64 exec, s[2:3]
	s_cbranch_execz .LBB0_12
	s_lshl_b32 s2, s86, 8
	s_bcnt1_i32_b64 s3, s[6:7]
	v_mov_b32_e32 v2, s2
	v_mov_b32_e32 v3, s3
	global_atomic_add v2, v3, s[84:85] offset:1024

.LBB0_231:
	v_mul_f32_e32 v144, 0xbfb8aa3b, v126
	v_exp_f32_e32 v145, v144
	v_mul_f32_e32 v144, 0xbfb8aa3b, v127
	v_exp_f32_e32 v152, v144
	v_mul_f32_e32 v153, 0xbfb8aa3b, v128
	v_add_f32_e32 v145, 1.0, v145
	v_rcp_f32_e32 v154, v145
	v_add_f32_e32 v145, 1.0, v152
	v_rcp_f32_e32 v155, v145
	v_exp_f32_e32 v153, v153
	v_lshl_or_b32 v144, s34, 7, v148
	v_ashrrev_i32_e32 v145, 31, v144
	v_pk_mul_f32 v[126:127], v[126:127], v[154:155]
	v_mul_f32_e32 v154, 0xbfb8aa3b, v129
	v_exp_f32_e32 v154, v154
	v_pk_mul_f32 v[118:119], v[126:127], v[118:119]
	v_add_f32_e32 v126, 1.0, v153
	v_mul_f32_e32 v153, 0xbfb8aa3b, v122
	v_add_f32_e32 v127, 1.0, v154
	v_rcp_f32_e32 v126, v126
	v_rcp_f32_e32 v127, v127
	v_exp_f32_e32 v153, v153
	v_mul_f32_e32 v154, 0xbfb8aa3b, v123
	v_exp_f32_e32 v154, v154
	v_pk_mul_f32 v[126:127], v[128:129], v[126:127]
	v_add_f32_e32 v128, 1.0, v153
	v_mul_f32_e32 v153, 0xbfb8aa3b, v124
	v_add_f32_e32 v129, 1.0, v154
	v_exp_f32_e32 v153, v153
	v_mul_f32_e32 v154, 0xbfb8aa3b, v125
	v_exp_f32_e32 v155, v154
	v_rcp_f32_e32 v128, v128
	v_add_f32_e32 v153, 1.0, v153
	v_rcp_f32_e32 v129, v129
	v_rcp_f32_e32 v154, v153
	v_add_f32_e32 v153, 1.0, v155
	v_rcp_f32_e32 v155, v153
	v_pk_mul_f32 v[122:123], v[122:123], v[128:129]
	v_lshl_add_u32 v152, s30, 8, v146
	v_pk_mul_f32 v[122:123], v[122:123], v[114:115]
	v_pk_mul_f32 v[114:115], v[124:125], v[154:155]
	v_lshl_add_u64 v[144:145], v[144:145], 1, s[72:73]
	v_pk_mul_f32 v[124:125], v[114:115], v[116:117]
	v_mul_f32_e32 v117, 0xbfb8aa3b, v110
	v_cvt_pk_bf16_f32 v114, v118, v119
	v_exp_f32_e32 v118, v117
	v_mul_f32_e32 v117, 0xbfb8aa3b, v111
	v_exp_f32_e32 v119, v117
	v_pk_mul_f32 v[120:121], v[126:127], v[120:121]
	v_cvt_pk_bf16_f32 v116, v122, v123
	v_cvt_pk_bf16_f32 v115, v120, v121
	v_cvt_pk_bf16_f32 v117, v124, v125
	v_pk_add_f32 v[118:119], v[118:119], s[100:101]
	v_mad_i64_i32 v[120:121], s[36:37], v152, s58, v[144:145]
	v_rcp_f32_e32 v118, v118
	v_rcp_f32_e32 v119, v119
	global_store_dwordx4 v[120:121], v[114:117], off
	v_pk_mul_f32 v[110:111], v[110:111], v[118:119]
	s_nop 0
	v_pk_mul_f32 v[114:115], v[112:113], s[98:99]
	v_exp_f32_e32 v114, v114
	v_exp_f32_e32 v115, v115
	v_pk_mul_f32 v[102:103], v[110:111], v[102:103]
	v_pk_add_f32 v[110:111], v[114:115], s[100:101]
	v_pk_mul_f32 v[114:115], v[106:107], s[98:99]
	v_rcp_f32_e32 v110, v110
	v_rcp_f32_e32 v111, v111
	v_exp_f32_e32 v114, v114
	v_exp_f32_e32 v115, v115
	v_pk_mul_f32 v[110:111], v[112:113], v[110:111]
	v_pk_add_f32 v[112:113], v[114:115], s[100:101]
	v_pk_mul_f32 v[114:115], v[108:109], s[98:99]
	v_exp_f32_e32 v114, v114
	v_exp_f32_e32 v115, v115
	v_rcp_f32_e32 v112, v112
	v_rcp_f32_e32 v113, v113
	v_pk_add_f32 v[114:115], v[114:115], s[100:101]
	v_rcp_f32_e32 v114, v114
	v_rcp_f32_e32 v115, v115
	v_pk_mul_f32 v[106:107], v[106:107], v[112:113]
	v_pk_mul_f32 v[104:105], v[110:111], v[104:105]
	v_pk_mul_f32 v[106:107], v[106:107], v[98:99]
	v_pk_mul_f32 v[98:99], v[108:109], v[114:115]
	s_nop 0
	v_pk_mul_f32 v[108:109], v[98:99], v[100:101]
	v_cvt_pk_bf16_f32 v98, v102, v103
	v_pk_mul_f32 v[102:103], v[94:95], s[98:99]
	v_exp_f32_e32 v102, v102
	v_exp_f32_e32 v103, v103
	v_cvt_pk_bf16_f32 v99, v104, v105
	v_or_b32_e32 v104, 16, v152
	v_cvt_pk_bf16_f32 v100, v106, v107
	v_cvt_pk_bf16_f32 v101, v108, v109
	v_pk_add_f32 v[102:103], v[102:103], s[100:101]
	v_mad_i64_i32 v[104:105], s[36:37], v104, s58, v[144:145]
	v_rcp_f32_e32 v102, v102
	v_rcp_f32_e32 v103, v103
	global_store_dwordx4 v[104:105], v[98:101], off
	v_pk_mul_f32 v[94:95], v[94:95], v[102:103]
	s_nop 0
	v_pk_mul_f32 v[98:99], v[96:97], s[98:99]
	v_exp_f32_e32 v98, v98
	v_exp_f32_e32 v99, v99
	v_pk_mul_f32 v[86:87], v[94:95], v[86:87]
	v_pk_add_f32 v[94:95], v[98:99], s[100:101]
	v_pk_mul_f32 v[98:99], v[90:91], s[98:99]
	v_rcp_f32_e32 v94, v94
	v_rcp_f32_e32 v95, v95
	v_exp_f32_e32 v98, v98
	v_exp_f32_e32 v99, v99
	v_pk_mul_f32 v[94:95], v[96:97], v[94:95]
	v_pk_add_f32 v[96:97], v[98:99], s[100:101]
	v_pk_mul_f32 v[98:99], v[92:93], s[98:99]
	v_exp_f32_e32 v98, v98
	v_exp_f32_e32 v99, v99
	v_rcp_f32_e32 v96, v96
	v_rcp_f32_e32 v97, v97
	v_pk_add_f32 v[98:99], v[98:99], s[100:101]
	v_rcp_f32_e32 v98, v98
	v_rcp_f32_e32 v99, v99
	v_pk_mul_f32 v[90:91], v[90:91], v[96:97]
	v_pk_mul_f32 v[88:89], v[94:95], v[88:89]
	v_pk_mul_f32 v[90:91], v[90:91], v[82:83]
	v_pk_mul_f32 v[82:83], v[92:93], v[98:99]
	s_nop 0
	v_pk_mul_f32 v[92:93], v[82:83], v[84:85]
	v_cvt_pk_bf16_f32 v82, v86, v87
	v_pk_mul_f32 v[86:87], v[78:79], s[98:99]
	v_exp_f32_e32 v86, v86
	v_exp_f32_e32 v87, v87
	v_cvt_pk_bf16_f32 v83, v88, v89
	v_or_b32_e32 v88, 32, v152
	v_cvt_pk_bf16_f32 v84, v90, v91
	v_cvt_pk_bf16_f32 v85, v92, v93
	v_pk_add_f32 v[86:87], v[86:87], s[100:101]
	v_mad_i64_i32 v[88:89], s[36:37], v88, s58, v[144:145]
	v_rcp_f32_e32 v86, v86
	v_rcp_f32_e32 v87, v87
	global_store_dwordx4 v[88:89], v[82:85], off
	v_pk_mul_f32 v[78:79], v[78:79], v[86:87]
	s_nop 0
	v_pk_mul_f32 v[82:83], v[80:81], s[98:99]
	v_exp_f32_e32 v82, v82
	v_exp_f32_e32 v83, v83
	v_pk_mul_f32 v[70:71], v[78:79], v[70:71]
	v_pk_add_f32 v[78:79], v[82:83], s[100:101]
	v_pk_mul_f32 v[82:83], v[74:75], s[98:99]
	v_rcp_f32_e32 v78, v78
	v_rcp_f32_e32 v79, v79
	v_exp_f32_e32 v82, v82
	v_exp_f32_e32 v83, v83
	v_pk_mul_f32 v[78:79], v[80:81], v[78:79]
	v_pk_add_f32 v[80:81], v[82:83], s[100:101]
	v_pk_mul_f32 v[82:83], v[76:77], s[98:99]
	v_exp_f32_e32 v82, v82
	v_exp_f32_e32 v83, v83
	v_rcp_f32_e32 v80, v80
	v_rcp_f32_e32 v81, v81
	v_pk_add_f32 v[82:83], v[82:83], s[100:101]
	v_rcp_f32_e32 v82, v82
	v_rcp_f32_e32 v83, v83
	v_pk_mul_f32 v[74:75], v[74:75], v[80:81]
	v_pk_mul_f32 v[72:73], v[78:79], v[72:73]
	v_pk_mul_f32 v[74:75], v[74:75], v[66:67]
	v_pk_mul_f32 v[66:67], v[76:77], v[82:83]
	s_nop 0
	v_pk_mul_f32 v[76:77], v[66:67], v[68:69]
	v_cvt_pk_bf16_f32 v66, v70, v71
	v_pk_mul_f32 v[70:71], v[62:63], s[98:99]
	v_exp_f32_e32 v70, v70
	v_exp_f32_e32 v71, v71
	v_cvt_pk_bf16_f32 v67, v72, v73
	v_or_b32_e32 v72, 48, v152
	v_cvt_pk_bf16_f32 v68, v74, v75
	v_cvt_pk_bf16_f32 v69, v76, v77
	v_pk_add_f32 v[70:71], v[70:71], s[100:101]
	v_mad_i64_i32 v[72:73], s[36:37], v72, s58, v[144:145]
	v_rcp_f32_e32 v70, v70
	v_rcp_f32_e32 v71, v71
	global_store_dwordx4 v[72:73], v[66:69], off
	v_pk_mul_f32 v[62:63], v[62:63], v[70:71]
	s_nop 0
	v_pk_mul_f32 v[66:67], v[64:65], s[98:99]
	v_exp_f32_e32 v66, v66
	v_exp_f32_e32 v67, v67
	v_pk_mul_f32 v[54:55], v[62:63], v[54:55]
	v_add_u32_e32 v68, 0x80, v152
	v_pk_add_f32 v[62:63], v[66:67], s[100:101]
	v_pk_mul_f32 v[66:67], v[58:59], s[98:99]
	v_rcp_f32_e32 v62, v62
	v_rcp_f32_e32 v63, v63
	v_exp_f32_e32 v66, v66
	v_exp_f32_e32 v67, v67
	v_pk_mul_f32 v[62:63], v[64:65], v[62:63]
	v_pk_add_f32 v[64:65], v[66:67], s[100:101]
	v_pk_mul_f32 v[66:67], v[60:61], s[98:99]
	v_exp_f32_e32 v66, v66
	v_exp_f32_e32 v67, v67
	v_rcp_f32_e32 v64, v64
	v_rcp_f32_e32 v65, v65
	v_pk_add_f32 v[66:67], v[66:67], s[100:101]
	v_rcp_f32_e32 v66, v66
	v_rcp_f32_e32 v67, v67
	v_pk_mul_f32 v[58:59], v[58:59], v[64:65]
	v_pk_mul_f32 v[56:57], v[62:63], v[56:57]
	v_pk_mul_f32 v[58:59], v[58:59], v[50:51]
	v_pk_mul_f32 v[50:51], v[60:61], v[66:67]
	s_nop 0
	v_pk_mul_f32 v[60:61], v[50:51], v[52:53]
	v_mul_f32_e32 v53, 0xbfb8aa3b, v46
	v_cvt_pk_bf16_f32 v50, v54, v55
	v_exp_f32_e32 v54, v53
	v_mul_f32_e32 v53, 0xbfb8aa3b, v47
	v_exp_f32_e32 v55, v53
	v_cvt_pk_bf16_f32 v51, v56, v57
	v_cvt_pk_bf16_f32 v52, v58, v59
	v_cvt_pk_bf16_f32 v53, v60, v61
	v_pk_add_f32 v[54:55], v[54:55], s[100:101]
	v_mad_i64_i32 v[56:57], s[36:37], v68, s58, v[144:145]
	v_rcp_f32_e32 v54, v54
	v_rcp_f32_e32 v55, v55
	global_store_dwordx4 v[56:57], v[50:53], off
	v_pk_mul_f32 v[46:47], v[46:47], v[54:55]
	s_nop 0
	v_pk_mul_f32 v[50:51], v[48:49], s[98:99]
	v_exp_f32_e32 v50, v50
	v_exp_f32_e32 v51, v51
	v_pk_mul_f32 v[38:39], v[46:47], v[38:39]
	v_pk_add_f32 v[46:47], v[50:51], s[100:101]
	v_pk_mul_f32 v[50:51], v[42:43], s[98:99]
	v_rcp_f32_e32 v46, v46
	v_rcp_f32_e32 v47, v47
	v_exp_f32_e32 v50, v50
	v_exp_f32_e32 v51, v51
	v_pk_mul_f32 v[46:47], v[48:49], v[46:47]
	v_pk_add_f32 v[48:49], v[50:51], s[100:101]
	v_pk_mul_f32 v[50:51], v[44:45], s[98:99]
	v_exp_f32_e32 v50, v50
	v_exp_f32_e32 v51, v51
	v_rcp_f32_e32 v48, v48
	v_rcp_f32_e32 v49, v49
	v_pk_add_f32 v[50:51], v[50:51], s[100:101]
	v_rcp_f32_e32 v50, v50
	v_rcp_f32_e32 v51, v51
	v_pk_mul_f32 v[42:43], v[42:43], v[48:49]
	v_pk_mul_f32 v[40:41], v[46:47], v[40:41]
	v_pk_mul_f32 v[42:43], v[42:43], v[34:35]
	v_pk_mul_f32 v[34:35], v[44:45], v[50:51]
	s_nop 0
	v_pk_mul_f32 v[44:45], v[34:35], v[36:37]
	v_cvt_pk_bf16_f32 v34, v38, v39
	v_pk_mul_f32 v[38:39], v[30:31], s[98:99]
	v_exp_f32_e32 v38, v38
	v_exp_f32_e32 v39, v39
	v_cvt_pk_bf16_f32 v35, v40, v41
	v_add_u32_e32 v40, 0x90, v152
	v_cvt_pk_bf16_f32 v36, v42, v43
	v_cvt_pk_bf16_f32 v37, v44, v45
	v_pk_add_f32 v[38:39], v[38:39], s[100:101]
	v_mad_i64_i32 v[40:41], s[36:37], v40, s58, v[144:145]
	v_rcp_f32_e32 v38, v38
	v_rcp_f32_e32 v39, v39
	global_store_dwordx4 v[40:41], v[34:37], off
	v_pk_mul_f32 v[30:31], v[30:31], v[38:39]
	s_nop 0
	v_pk_mul_f32 v[34:35], v[32:33], s[98:99]
	v_exp_f32_e32 v34, v34
	v_exp_f32_e32 v35, v35
	v_pk_mul_f32 v[22:23], v[30:31], v[22:23]
	v_pk_add_f32 v[30:31], v[34:35], s[100:101]
	v_pk_mul_f32 v[34:35], v[26:27], s[98:99]
	v_rcp_f32_e32 v30, v30
	v_rcp_f32_e32 v31, v31
	v_exp_f32_e32 v34, v34
	v_exp_f32_e32 v35, v35
	v_pk_mul_f32 v[30:31], v[32:33], v[30:31]
	v_pk_add_f32 v[32:33], v[34:35], s[100:101]
	v_pk_mul_f32 v[34:35], v[28:29], s[98:99]
	v_exp_f32_e32 v34, v34
	v_exp_f32_e32 v35, v35
	v_rcp_f32_e32 v32, v32
	v_rcp_f32_e32 v33, v33
	v_pk_add_f32 v[34:35], v[34:35], s[100:101]
	v_rcp_f32_e32 v34, v34
	v_rcp_f32_e32 v35, v35
	v_pk_mul_f32 v[26:27], v[26:27], v[32:33]
	v_pk_mul_f32 v[24:25], v[30:31], v[24:25]
	v_pk_mul_f32 v[26:27], v[26:27], v[18:19]
	v_pk_mul_f32 v[18:19], v[28:29], v[34:35]
	s_nop 0
	v_pk_mul_f32 v[28:29], v[18:19], v[20:21]
	v_cvt_pk_bf16_f32 v18, v22, v23
	v_pk_mul_f32 v[22:23], v[14:15], s[98:99]
	v_exp_f32_e32 v22, v22
	v_exp_f32_e32 v23, v23
	v_cvt_pk_bf16_f32 v19, v24, v25
	v_add_u32_e32 v24, 0xa0, v152
	v_cvt_pk_bf16_f32 v20, v26, v27
	v_cvt_pk_bf16_f32 v21, v28, v29
	v_pk_add_f32 v[22:23], v[22:23], s[100:101]
	v_mad_i64_i32 v[24:25], s[36:37], v24, s58, v[144:145]
	v_rcp_f32_e32 v22, v22
	v_rcp_f32_e32 v23, v23
	global_store_dwordx4 v[24:25], v[18:21], off
	v_pk_mul_f32 v[14:15], v[14:15], v[22:23]
	s_nop 0
	v_pk_mul_f32 v[18:19], v[16:17], s[98:99]
	v_exp_f32_e32 v18, v18
	v_exp_f32_e32 v19, v19
	v_pk_mul_f32 v[6:7], v[14:15], v[6:7]
	v_pk_add_f32 v[14:15], v[18:19], s[100:101]
	v_pk_mul_f32 v[18:19], v[10:11], s[98:99]
	v_rcp_f32_e32 v14, v14
	v_rcp_f32_e32 v15, v15
	v_exp_f32_e32 v18, v18
	v_exp_f32_e32 v19, v19
	v_pk_mul_f32 v[14:15], v[16:17], v[14:15]
	v_pk_add_f32 v[16:17], v[18:19], s[100:101]
	v_pk_mul_f32 v[18:19], v[12:13], s[98:99]
	v_exp_f32_e32 v18, v18
	v_exp_f32_e32 v19, v19
	v_rcp_f32_e32 v16, v16
	v_rcp_f32_e32 v17, v17
	v_pk_add_f32 v[18:19], v[18:19], s[100:101]
	v_rcp_f32_e32 v18, v18
	v_rcp_f32_e32 v19, v19
	v_pk_mul_f32 v[10:11], v[10:11], v[16:17]
	v_pk_mul_f32 v[8:9], v[14:15], v[8:9]
	v_pk_mul_f32 v[10:11], v[10:11], v[2:3]
	v_pk_mul_f32 v[2:3], v[12:13], v[18:19]
	s_nop 0
	v_pk_mul_f32 v[12:13], v[2:3], v[4:5]
	v_cvt_pk_bf16_f32 v2, v6, v7
	v_add_u32_e32 v6, 0xb0, v152
	v_cvt_pk_bf16_f32 v3, v8, v9
	v_cvt_pk_bf16_f32 v4, v10, v11
	v_cvt_pk_bf16_f32 v5, v12, v13
	v_mad_i64_i32 v[6:7], s[36:37], v6, s58, v[144:145]
	global_store_dwordx4 v[6:7], v[2:5], off
	s_cmp_eq_u32 s31, 8
	s_mov_b64 s[30:31], -1
	s_cbranch_scc1 .LBB0_210

.LBB0_1325:
	v_mul_f32_e32 v144, 0xbfb8aa3b, v126
	v_exp_f32_e32 v145, v144
	v_mul_f32_e32 v144, 0xbfb8aa3b, v127
	v_exp_f32_e32 v151, v144
	v_lshl_or_b32 v144, s26, 7, v147
	v_add_f32_e32 v145, 1.0, v145
	v_rcp_f32_e32 v152, v145
	v_add_f32_e32 v145, 1.0, v151
	v_rcp_f32_e32 v153, v145
	v_ashrrev_i32_e32 v145, 31, v144
	v_lshl_add_u32 v151, s24, 8, v1
	v_lshl_add_u64 v[144:145], v[144:145], 1, s[72:73]
	v_pk_mul_f32 v[126:127], v[126:127], v[152:153]
	v_pk_mul_f32 v[152:153], v[128:129], s[98:99]
	v_exp_f32_e32 v152, v152
	v_exp_f32_e32 v153, v153
	v_pk_mul_f32 v[118:119], v[126:127], v[118:119]
	v_pk_add_f32 v[126:127], v[152:153], s[100:101]
	v_pk_mul_f32 v[152:153], v[122:123], s[98:99]
	v_rcp_f32_e32 v126, v126
	v_rcp_f32_e32 v127, v127
	v_exp_f32_e32 v152, v152
	v_exp_f32_e32 v153, v153
	v_pk_mul_f32 v[126:127], v[128:129], v[126:127]
	v_pk_add_f32 v[128:129], v[152:153], s[100:101]
	v_pk_mul_f32 v[152:153], v[124:125], s[98:99]
	v_exp_f32_e32 v152, v152
	v_exp_f32_e32 v153, v153
	v_rcp_f32_e32 v128, v128
	v_rcp_f32_e32 v129, v129
	v_pk_add_f32 v[152:153], v[152:153], s[100:101]
	v_rcp_f32_e32 v152, v152
	v_rcp_f32_e32 v153, v153
	v_pk_mul_f32 v[122:123], v[122:123], v[128:129]
	v_pk_mul_f32 v[120:121], v[126:127], v[120:121]
	v_pk_mul_f32 v[122:123], v[122:123], v[114:115]
	v_pk_mul_f32 v[114:115], v[124:125], v[152:153]
	s_nop 0
	v_pk_mul_f32 v[124:125], v[114:115], v[116:117]
	v_mul_f32_e32 v117, 0xbfb8aa3b, v110
	v_cvt_pk_bf16_f32 v114, v118, v119
	v_exp_f32_e32 v118, v117
	v_mul_f32_e32 v117, 0xbfb8aa3b, v111
	v_exp_f32_e32 v119, v117
	v_cvt_pk_bf16_f32 v115, v120, v121
	v_cvt_pk_bf16_f32 v116, v122, v123
	v_cvt_pk_bf16_f32 v117, v124, v125
	v_pk_add_f32 v[118:119], v[118:119], s[100:101]
	v_mad_i64_i32 v[120:121], s[28:29], v151, s64, v[144:145]
	v_rcp_f32_e32 v118, v118
	v_rcp_f32_e32 v119, v119
	global_store_dwordx4 v[120:121], v[114:117], off
	v_pk_mul_f32 v[110:111], v[110:111], v[118:119]
	s_nop 0
	v_pk_mul_f32 v[114:115], v[112:113], s[98:99]
	v_exp_f32_e32 v114, v114
	v_exp_f32_e32 v115, v115
	v_pk_mul_f32 v[102:103], v[110:111], v[102:103]
	v_pk_add_f32 v[110:111], v[114:115], s[100:101]
	v_pk_mul_f32 v[114:115], v[106:107], s[98:99]
	v_rcp_f32_e32 v110, v110
	v_rcp_f32_e32 v111, v111
	v_exp_f32_e32 v114, v114
	v_exp_f32_e32 v115, v115
	v_pk_mul_f32 v[110:111], v[112:113], v[110:111]
	v_pk_add_f32 v[112:113], v[114:115], s[100:101]
	v_pk_mul_f32 v[114:115], v[108:109], s[98:99]
	v_exp_f32_e32 v114, v114
	v_exp_f32_e32 v115, v115
	v_rcp_f32_e32 v112, v112
	v_rcp_f32_e32 v113, v113
	v_pk_add_f32 v[114:115], v[114:115], s[100:101]
	v_rcp_f32_e32 v114, v114
	v_rcp_f32_e32 v115, v115
	v_pk_mul_f32 v[106:107], v[106:107], v[112:113]
	v_pk_mul_f32 v[104:105], v[110:111], v[104:105]
	v_pk_mul_f32 v[106:107], v[106:107], v[98:99]
	v_pk_mul_f32 v[98:99], v[108:109], v[114:115]
	s_nop 0
	v_pk_mul_f32 v[108:109], v[98:99], v[100:101]
	v_cvt_pk_bf16_f32 v98, v102, v103
	v_pk_mul_f32 v[102:103], v[94:95], s[98:99]
	v_exp_f32_e32 v102, v102
	v_exp_f32_e32 v103, v103
	v_cvt_pk_bf16_f32 v99, v104, v105
	v_or_b32_e32 v104, 16, v151
	v_cvt_pk_bf16_f32 v100, v106, v107
	v_cvt_pk_bf16_f32 v101, v108, v109
	v_pk_add_f32 v[102:103], v[102:103], s[100:101]
	v_mad_i64_i32 v[104:105], s[28:29], v104, s64, v[144:145]
	v_rcp_f32_e32 v102, v102
	v_rcp_f32_e32 v103, v103
	global_store_dwordx4 v[104:105], v[98:101], off
	v_pk_mul_f32 v[94:95], v[94:95], v[102:103]
	s_nop 0
	v_pk_mul_f32 v[98:99], v[96:97], s[98:99]
	v_exp_f32_e32 v98, v98
	v_exp_f32_e32 v99, v99
	v_pk_mul_f32 v[86:87], v[94:95], v[86:87]
	v_pk_add_f32 v[94:95], v[98:99], s[100:101]
	v_pk_mul_f32 v[98:99], v[90:91], s[98:99]
	v_rcp_f32_e32 v94, v94
	v_rcp_f32_e32 v95, v95
	v_exp_f32_e32 v98, v98
	v_exp_f32_e32 v99, v99
	v_pk_mul_f32 v[94:95], v[96:97], v[94:95]
	v_pk_add_f32 v[96:97], v[98:99], s[100:101]
	v_pk_mul_f32 v[98:99], v[92:93], s[98:99]
	v_exp_f32_e32 v98, v98
	v_exp_f32_e32 v99, v99
	v_rcp_f32_e32 v96, v96
	v_rcp_f32_e32 v97, v97
	v_pk_add_f32 v[98:99], v[98:99], s[100:101]
	v_rcp_f32_e32 v98, v98
	v_rcp_f32_e32 v99, v99
	v_pk_mul_f32 v[90:91], v[90:91], v[96:97]
	v_pk_mul_f32 v[88:89], v[94:95], v[88:89]
	v_pk_mul_f32 v[90:91], v[90:91], v[82:83]
	v_pk_mul_f32 v[82:83], v[92:93], v[98:99]
	s_nop 0
	v_pk_mul_f32 v[92:93], v[82:83], v[84:85]
	v_cvt_pk_bf16_f32 v82, v86, v87
	v_pk_mul_f32 v[86:87], v[78:79], s[98:99]
	v_exp_f32_e32 v86, v86
	v_exp_f32_e32 v87, v87
	v_cvt_pk_bf16_f32 v83, v88, v89
	v_or_b32_e32 v88, 32, v151
	v_cvt_pk_bf16_f32 v84, v90, v91
	v_cvt_pk_bf16_f32 v85, v92, v93
	v_pk_add_f32 v[86:87], v[86:87], s[100:101]
	v_mad_i64_i32 v[88:89], s[28:29], v88, s64, v[144:145]
	v_rcp_f32_e32 v86, v86
	v_rcp_f32_e32 v87, v87
	global_store_dwordx4 v[88:89], v[82:85], off
	v_pk_mul_f32 v[78:79], v[78:79], v[86:87]
	s_nop 0
	v_pk_mul_f32 v[82:83], v[80:81], s[98:99]
	v_exp_f32_e32 v82, v82
	v_exp_f32_e32 v83, v83
	v_pk_mul_f32 v[70:71], v[78:79], v[70:71]
	v_pk_add_f32 v[78:79], v[82:83], s[100:101]
	v_pk_mul_f32 v[82:83], v[74:75], s[98:99]
	v_rcp_f32_e32 v78, v78
	v_rcp_f32_e32 v79, v79
	v_exp_f32_e32 v82, v82
	v_exp_f32_e32 v83, v83
	v_pk_mul_f32 v[78:79], v[80:81], v[78:79]
	v_pk_add_f32 v[80:81], v[82:83], s[100:101]
	v_pk_mul_f32 v[82:83], v[76:77], s[98:99]
	v_exp_f32_e32 v82, v82
	v_exp_f32_e32 v83, v83
	v_rcp_f32_e32 v80, v80
	v_rcp_f32_e32 v81, v81
	v_pk_add_f32 v[82:83], v[82:83], s[100:101]
	v_rcp_f32_e32 v82, v82
	v_rcp_f32_e32 v83, v83
	v_pk_mul_f32 v[74:75], v[74:75], v[80:81]
	v_pk_mul_f32 v[72:73], v[78:79], v[72:73]
	v_pk_mul_f32 v[74:75], v[74:75], v[66:67]
	v_pk_mul_f32 v[66:67], v[76:77], v[82:83]
	s_nop 0
	v_pk_mul_f32 v[76:77], v[66:67], v[68:69]
	v_cvt_pk_bf16_f32 v66, v70, v71
	v_pk_mul_f32 v[70:71], v[62:63], s[98:99]
	v_exp_f32_e32 v70, v70
	v_exp_f32_e32 v71, v71
	v_cvt_pk_bf16_f32 v67, v72, v73
	v_or_b32_e32 v72, 48, v151
	v_cvt_pk_bf16_f32 v68, v74, v75
	v_cvt_pk_bf16_f32 v69, v76, v77
	v_pk_add_f32 v[70:71], v[70:71], s[100:101]
	v_mad_i64_i32 v[72:73], s[28:29], v72, s64, v[144:145]
	v_rcp_f32_e32 v70, v70
	v_rcp_f32_e32 v71, v71
	global_store_dwordx4 v[72:73], v[66:69], off
	v_pk_mul_f32 v[62:63], v[62:63], v[70:71]
	s_nop 0
	v_pk_mul_f32 v[66:67], v[64:65], s[98:99]
	v_exp_f32_e32 v66, v66
	v_exp_f32_e32 v67, v67
	v_pk_mul_f32 v[54:55], v[62:63], v[54:55]
	v_add_u32_e32 v68, 0x80, v151
	v_pk_add_f32 v[62:63], v[66:67], s[100:101]
	v_pk_mul_f32 v[66:67], v[58:59], s[98:99]
	v_rcp_f32_e32 v62, v62
	v_rcp_f32_e32 v63, v63
	v_exp_f32_e32 v66, v66
	v_exp_f32_e32 v67, v67
	v_pk_mul_f32 v[62:63], v[64:65], v[62:63]
	v_pk_add_f32 v[64:65], v[66:67], s[100:101]
	v_pk_mul_f32 v[66:67], v[60:61], s[98:99]
	v_exp_f32_e32 v66, v66
	v_exp_f32_e32 v67, v67
	v_rcp_f32_e32 v64, v64
	v_rcp_f32_e32 v65, v65
	v_pk_add_f32 v[66:67], v[66:67], s[100:101]
	v_rcp_f32_e32 v66, v66
	v_rcp_f32_e32 v67, v67
	v_pk_mul_f32 v[58:59], v[58:59], v[64:65]
	v_pk_mul_f32 v[56:57], v[62:63], v[56:57]
	v_pk_mul_f32 v[58:59], v[58:59], v[50:51]
	v_pk_mul_f32 v[50:51], v[60:61], v[66:67]
	s_nop 0
	v_pk_mul_f32 v[60:61], v[50:51], v[52:53]
	v_mul_f32_e32 v53, 0xbfb8aa3b, v46
	v_cvt_pk_bf16_f32 v50, v54, v55
	v_exp_f32_e32 v54, v53
	v_mul_f32_e32 v53, 0xbfb8aa3b, v47
	v_exp_f32_e32 v55, v53
	v_cvt_pk_bf16_f32 v51, v56, v57
	v_cvt_pk_bf16_f32 v52, v58, v59
	v_cvt_pk_bf16_f32 v53, v60, v61
	v_pk_add_f32 v[54:55], v[54:55], s[100:101]
	v_mad_i64_i32 v[56:57], s[28:29], v68, s64, v[144:145]
	v_rcp_f32_e32 v54, v54
	v_rcp_f32_e32 v55, v55
	global_store_dwordx4 v[56:57], v[50:53], off
	v_pk_mul_f32 v[46:47], v[46:47], v[54:55]
	s_nop 0
	v_pk_mul_f32 v[50:51], v[48:49], s[98:99]
	v_exp_f32_e32 v50, v50
	v_exp_f32_e32 v51, v51
	v_pk_mul_f32 v[38:39], v[46:47], v[38:39]
	v_pk_add_f32 v[46:47], v[50:51], s[100:101]
	v_pk_mul_f32 v[50:51], v[42:43], s[98:99]
	v_rcp_f32_e32 v46, v46
	v_rcp_f32_e32 v47, v47
	v_exp_f32_e32 v50, v50
	v_exp_f32_e32 v51, v51
	v_pk_mul_f32 v[46:47], v[48:49], v[46:47]
	v_pk_add_f32 v[48:49], v[50:51], s[100:101]
	v_pk_mul_f32 v[50:51], v[44:45], s[98:99]
	v_exp_f32_e32 v50, v50
	v_exp_f32_e32 v51, v51
	v_rcp_f32_e32 v48, v48
	v_rcp_f32_e32 v49, v49
	v_pk_add_f32 v[50:51], v[50:51], s[100:101]
	v_rcp_f32_e32 v50, v50
	v_rcp_f32_e32 v51, v51
	v_pk_mul_f32 v[42:43], v[42:43], v[48:49]
	v_pk_mul_f32 v[40:41], v[46:47], v[40:41]
	v_pk_mul_f32 v[42:43], v[42:43], v[34:35]
	v_pk_mul_f32 v[34:35], v[44:45], v[50:51]
	s_nop 0
	v_pk_mul_f32 v[44:45], v[34:35], v[36:37]
	v_cvt_pk_bf16_f32 v34, v38, v39
	v_pk_mul_f32 v[38:39], v[30:31], s[98:99]
	v_exp_f32_e32 v38, v38
	v_exp_f32_e32 v39, v39
	v_cvt_pk_bf16_f32 v35, v40, v41
	v_add_u32_e32 v40, 0x90, v151
	v_cvt_pk_bf16_f32 v36, v42, v43
	v_cvt_pk_bf16_f32 v37, v44, v45
	v_pk_add_f32 v[38:39], v[38:39], s[100:101]
	v_mad_i64_i32 v[40:41], s[28:29], v40, s64, v[144:145]
	v_rcp_f32_e32 v38, v38
	v_rcp_f32_e32 v39, v39
	global_store_dwordx4 v[40:41], v[34:37], off
	v_pk_mul_f32 v[30:31], v[30:31], v[38:39]
	s_nop 0
	v_pk_mul_f32 v[34:35], v[32:33], s[98:99]
	v_exp_f32_e32 v34, v34
	v_exp_f32_e32 v35, v35
	v_pk_mul_f32 v[22:23], v[30:31], v[22:23]
	v_pk_add_f32 v[30:31], v[34:35], s[100:101]
	v_pk_mul_f32 v[34:35], v[26:27], s[98:99]
	v_rcp_f32_e32 v30, v30
	v_rcp_f32_e32 v31, v31
	v_exp_f32_e32 v34, v34
	v_exp_f32_e32 v35, v35
	v_pk_mul_f32 v[30:31], v[32:33], v[30:31]
	v_pk_add_f32 v[32:33], v[34:35], s[100:101]
	v_pk_mul_f32 v[34:35], v[28:29], s[98:99]
	v_exp_f32_e32 v34, v34
	v_exp_f32_e32 v35, v35
	v_rcp_f32_e32 v32, v32
	v_rcp_f32_e32 v33, v33
	v_pk_add_f32 v[34:35], v[34:35], s[100:101]
	v_rcp_f32_e32 v34, v34
	v_rcp_f32_e32 v35, v35
	v_pk_mul_f32 v[26:27], v[26:27], v[32:33]
	v_pk_mul_f32 v[24:25], v[30:31], v[24:25]
	v_pk_mul_f32 v[26:27], v[26:27], v[18:19]
	v_pk_mul_f32 v[18:19], v[28:29], v[34:35]
	s_nop 0
	v_pk_mul_f32 v[28:29], v[18:19], v[20:21]
	v_cvt_pk_bf16_f32 v18, v22, v23
	v_pk_mul_f32 v[22:23], v[14:15], s[98:99]
	v_exp_f32_e32 v22, v22
	v_exp_f32_e32 v23, v23
	v_cvt_pk_bf16_f32 v19, v24, v25
	v_add_u32_e32 v24, 0xa0, v151
	v_cvt_pk_bf16_f32 v20, v26, v27
	v_cvt_pk_bf16_f32 v21, v28, v29
	v_pk_add_f32 v[22:23], v[22:23], s[100:101]
	v_mad_i64_i32 v[24:25], s[28:29], v24, s64, v[144:145]
	v_rcp_f32_e32 v22, v22
	v_rcp_f32_e32 v23, v23
	global_store_dwordx4 v[24:25], v[18:21], off
	v_pk_mul_f32 v[14:15], v[14:15], v[22:23]
	s_nop 0
	v_pk_mul_f32 v[18:19], v[16:17], s[98:99]
	v_exp_f32_e32 v18, v18
	v_exp_f32_e32 v19, v19
	v_pk_mul_f32 v[6:7], v[14:15], v[6:7]
	v_pk_add_f32 v[14:15], v[18:19], s[100:101]
	v_pk_mul_f32 v[18:19], v[10:11], s[98:99]
	v_rcp_f32_e32 v14, v14
	v_rcp_f32_e32 v15, v15
	v_exp_f32_e32 v18, v18
	v_exp_f32_e32 v19, v19
	v_pk_mul_f32 v[14:15], v[16:17], v[14:15]
	v_pk_add_f32 v[16:17], v[18:19], s[100:101]
	v_pk_mul_f32 v[18:19], v[12:13], s[98:99]
	v_exp_f32_e32 v18, v18
	v_exp_f32_e32 v19, v19
	v_rcp_f32_e32 v16, v16
	v_rcp_f32_e32 v17, v17
	v_pk_add_f32 v[18:19], v[18:19], s[100:101]
	v_rcp_f32_e32 v18, v18
	v_rcp_f32_e32 v19, v19
	v_pk_mul_f32 v[10:11], v[10:11], v[16:17]
	v_pk_mul_f32 v[8:9], v[14:15], v[8:9]
	v_pk_mul_f32 v[10:11], v[10:11], v[2:3]
	v_pk_mul_f32 v[2:3], v[12:13], v[18:19]
	s_nop 0
	v_pk_mul_f32 v[12:13], v[2:3], v[4:5]
	v_cvt_pk_bf16_f32 v2, v6, v7
	v_add_u32_e32 v6, 0xb0, v151
	v_cvt_pk_bf16_f32 v3, v8, v9
	v_cvt_pk_bf16_f32 v4, v10, v11
	v_cvt_pk_bf16_f32 v5, v12, v13
	v_mad_i64_i32 v[6:7], s[28:29], v6, s64, v[144:145]
	global_store_dwordx4 v[6:7], v[2:5], off
	s_cmp_eq_u32 s25, 8
	s_mov_b64 s[24:25], -1
	s_cbranch_scc1 .LBB0_1304

.LBB0_1382:
	s_ashr_i32 s4, s3, 31
	s_lshr_b32 s4, s4, 26
	s_add_i32 s4, s3, s4
	s_ashr_i32 s7, s4, 6
	s_and_b32 s6, s4, 0xffffffc0
	s_and_b32 s17, s4, 0xffffff80
	s_sub_i32 s6, s3, s6
	s_lshl_b32 s4, s7, 1
	s_lshl_b32 s8, s7, 14
	s_and_b32 s9, s6, 7
	s_and_b32 s18, s4, 2
	s_add_i32 s4, s6, 0xc0
	s_add_i32 s10, s6, 0x800
	s_and_b32 s14, s8, 0xffff8000
	s_ashr_i32 s7, s6, 31
	s_or_b32 s15, s8, 0x4000
	s_mul_i32 s12, s9, 0x108
	s_lshl_b64 s[8:9], s[4:5], 17
	s_lshl_b32 s19, s18, 12
	s_lshr_b32 s13, s10, 3
	s_lshl_b64 s[10:11], s[6:7], 17
	s_add_i32 s4, s6, 64
	v_lshl_add_u64 v[6:7], v[4:5], 0, s[8:9]
	s_or_b32 s8, s19, s14
	s_or_b32 s20, s18, 1
	s_add_i32 s21, s13, s12
	v_lshl_add_u64 v[8:9], v[4:5], 0, s[10:11]
	s_or_b32 s10, s19, s15
	s_lshl_b64 s[12:13], s[4:5], 17
	s_add_i32 s4, s6, 0x80
	s_ashr_i32 s9, s8, 31
	s_lshl_b32 s19, s20, 12
	s_ashr_i32 s11, s10, 31
	s_lshl_b64 s[6:7], s[4:5], 17
	s_lshl_b64 s[8:9], s[8:9], 1
	v_lshl_add_u64 v[44:45], v[4:5], 0, s[12:13]
	s_or_b32 s12, s19, s14
	s_lshl_b64 s[10:11], s[10:11], 1
	v_lshl_add_u64 v[46:47], v[4:5], 0, s[6:7]
	v_lshl_add_u64 v[36:37], v[8:9], 0, s[8:9]
	s_or_b32 s14, s19, s15
	s_ashr_i32 s13, s12, 31
	v_lshl_add_u64 v[38:39], v[8:9], 0, s[10:11]
	v_lshl_add_u64 v[40:41], v[44:45], 0, s[8:9]
	v_lshl_add_u64 v[42:43], v[44:45], 0, s[10:11]
	v_lshl_add_u64 v[48:49], v[46:47], 0, s[8:9]
	v_lshl_add_u64 v[50:51], v[46:47], 0, s[10:11]
	global_load_dwordx4 v[12:15], v[36:37], off
	global_load_dwordx4 v[16:19], v[38:39], off
	global_load_dwordx4 v[20:23], v[40:41], off
	global_load_dwordx4 v[24:27], v[42:43], off
	global_load_dwordx4 v[28:31], v[48:49], off
	global_load_dwordx4 v[32:35], v[50:51], off
	s_ashr_i32 s15, s14, 31
	v_lshl_add_u64 v[52:53], v[6:7], 0, s[8:9]
	s_lshl_b64 s[6:7], s[12:13], 1
	v_lshl_add_u64 v[54:55], v[6:7], 0, s[10:11]
	s_lshl_b64 s[8:9], s[14:15], 1
	global_load_dwordx4 v[36:39], v[52:53], off
	global_load_dwordx4 v[40:43], v[54:55], off
	v_lshl_add_u64 v[76:77], v[8:9], 0, s[6:7]
	v_lshl_add_u64 v[8:9], v[8:9], 0, s[8:9]
	v_lshl_add_u64 v[78:79], v[44:45], 0, s[6:7]
	v_lshl_add_u64 v[80:81], v[44:45], 0, s[8:9]
	v_lshl_add_u64 v[82:83], v[46:47], 0, s[6:7]
	v_lshl_add_u64 v[84:85], v[46:47], 0, s[8:9]
	v_lshl_add_u64 v[86:87], v[6:7], 0, s[6:7]
	v_lshl_add_u64 v[6:7], v[6:7], 0, s[8:9]
	global_load_dwordx4 v[44:47], v[76:77], off
	global_load_dwordx4 v[48:51], v[8:9], off
	global_load_dwordx4 v[52:55], v[78:79], off
	global_load_dwordx4 v[56:59], v[80:81], off
	global_load_dwordx4 v[60:63], v[82:83], off
	global_load_dwordx4 v[64:67], v[84:85], off
	global_load_dwordx4 v[68:71], v[86:87], off
	global_load_dwordx4 v[72:75], v[6:7], off
	s_and_b32 s22, s21, 0xffff
	s_mul_i32 s22, s22, 0xba2f
	s_lshr_b32 s4, s22, 24
	s_mul_i32 s10, s4, 0x160
	s_sub_i32 s6, s21, s10
	s_and_b32 s7, s6, 7
	s_lshl_b32 s4, s4, 11
	s_lshl_b32 s6, s6, 4
	s_lshl_b32 s7, s7, 8
	s_and_b32 s6, s6, 0x1f80
	s_or_b32 s4, s4, s7
	v_or_b32_e32 v2, s6, v1
	s_add_i32 s4, s4, s17
	v_lshlrev_b32_e32 v2, 1, v2
	v_add_u32_e32 v8, s4, v10
	v_lshl_add_u64 v[6:7], s[72:73], 0, v[2:3]
	v_lshl_or_b32 v2, s18, 4, v8
	v_lshl_or_b32 v11, s20, 4, v8
	v_mad_i64_i32 v[8:9], s[6:7], v2, s2, v[6:7]
	v_mad_i64_i32 v[6:7], s[6:7], v11, s2, v[6:7]
	s_add_i32 s16, s3, 0x100
	s_cmp_lt_i32 s3, 0
	s_mov_b32 s3, s16
	s_waitcnt vmcnt(0)
	v_lshlrev_b32_e32 v76, 16, v12
	v_and_b32_e32 v77, 0xffff0000, v12
	v_lshlrev_b32_e32 v12, 16, v13
	v_and_b32_e32 v13, 0xffff0000, v13
	v_lshlrev_b32_e32 v78, 16, v14
	v_and_b32_e32 v79, 0xffff0000, v14
	v_lshlrev_b32_e32 v14, 16, v15
	v_and_b32_e32 v15, 0xffff0000, v15
	v_lshlrev_b32_e32 v80, 16, v16
	v_and_b32_e32 v81, 0xffff0000, v16
	v_lshlrev_b32_e32 v16, 16, v17
	v_and_b32_e32 v17, 0xffff0000, v17
	v_lshlrev_b32_e32 v82, 16, v18
	v_and_b32_e32 v83, 0xffff0000, v18
	v_lshlrev_b32_e32 v18, 16, v19
	v_and_b32_e32 v19, 0xffff0000, v19
	v_lshlrev_b32_e32 v84, 16, v20
	v_and_b32_e32 v85, 0xffff0000, v20
	v_lshlrev_b32_e32 v20, 16, v21
	v_and_b32_e32 v21, 0xffff0000, v21
	v_lshlrev_b32_e32 v86, 16, v22
	v_and_b32_e32 v87, 0xffff0000, v22
	v_lshlrev_b32_e32 v22, 16, v23
	v_and_b32_e32 v23, 0xffff0000, v23
	v_lshlrev_b32_e32 v88, 16, v24
	v_and_b32_e32 v89, 0xffff0000, v24
	v_lshlrev_b32_e32 v24, 16, v25
	v_and_b32_e32 v25, 0xffff0000, v25
	v_lshlrev_b32_e32 v90, 16, v26
	v_and_b32_e32 v91, 0xffff0000, v26
	v_lshlrev_b32_e32 v26, 16, v27
	v_and_b32_e32 v27, 0xffff0000, v27
	v_pk_add_f32 v[76:77], v[76:77], 0 op_sel_hi:[1,0]
	v_pk_add_f32 v[12:13], v[12:13], 0 op_sel_hi:[1,0]
	v_pk_add_f32 v[78:79], v[78:79], 0 op_sel_hi:[1,0]
	v_pk_add_f32 v[14:15], v[14:15], 0 op_sel_hi:[1,0]
	v_pk_add_f32 v[16:17], v[16:17], 0 op_sel_hi:[1,0]
	v_pk_add_f32 v[18:19], v[18:19], 0 op_sel_hi:[1,0]
	v_lshlrev_b32_e32 v108, 16, v44
	v_and_b32_e32 v109, 0xffff0000, v44
	v_lshlrev_b32_e32 v44, 16, v45
	v_and_b32_e32 v45, 0xffff0000, v45
	v_lshlrev_b32_e32 v110, 16, v46
	v_and_b32_e32 v111, 0xffff0000, v46
	v_lshlrev_b32_e32 v46, 16, v47
	v_and_b32_e32 v47, 0xffff0000, v47
	v_lshlrev_b32_e32 v92, 16, v28
	v_and_b32_e32 v93, 0xffff0000, v28
	v_lshlrev_b32_e32 v28, 16, v29
	v_and_b32_e32 v29, 0xffff0000, v29
	v_lshlrev_b32_e32 v94, 16, v30
	v_and_b32_e32 v95, 0xffff0000, v30
	v_lshlrev_b32_e32 v30, 16, v31
	v_and_b32_e32 v31, 0xffff0000, v31
	v_lshlrev_b32_e32 v96, 16, v32
	v_and_b32_e32 v97, 0xffff0000, v32
	v_lshlrev_b32_e32 v32, 16, v33
	v_and_b32_e32 v33, 0xffff0000, v33
	v_lshlrev_b32_e32 v98, 16, v34
	v_and_b32_e32 v99, 0xffff0000, v34
	v_lshlrev_b32_e32 v34, 16, v35
	v_and_b32_e32 v35, 0xffff0000, v35
	v_pk_add_f32 v[80:81], v[80:81], 0 op_sel_hi:[1,0]
	v_lshlrev_b32_e32 v112, 16, v48
	v_and_b32_e32 v113, 0xffff0000, v48
	v_lshlrev_b32_e32 v48, 16, v49
	v_and_b32_e32 v49, 0xffff0000, v49
	v_lshlrev_b32_e32 v114, 16, v50
	v_and_b32_e32 v115, 0xffff0000, v50
	v_lshlrev_b32_e32 v50, 16, v51
	v_and_b32_e32 v51, 0xffff0000, v51
	v_lshlrev_b32_e32 v116, 16, v52
	v_and_b32_e32 v117, 0xffff0000, v52
	v_lshlrev_b32_e32 v52, 16, v53
	v_and_b32_e32 v53, 0xffff0000, v53
	v_lshlrev_b32_e32 v118, 16, v54
	v_and_b32_e32 v119, 0xffff0000, v54
	v_lshlrev_b32_e32 v54, 16, v55
	v_and_b32_e32 v55, 0xffff0000, v55
	v_pk_add_f32 v[12:13], v[12:13], v[20:21]
	v_pk_add_f32 v[20:21], v[76:77], v[84:85]
	v_pk_add_f32 v[14:15], v[14:15], v[22:23]
	v_pk_add_f32 v[22:23], v[78:79], v[86:87]
	v_pk_add_f32 v[16:17], v[16:17], v[24:25]
	v_pk_add_f32 v[18:19], v[18:19], v[26:27]
	v_pk_add_f32 v[76:77], v[108:109], 0 op_sel_hi:[1,0]
	v_pk_add_f32 v[44:45], v[44:45], 0 op_sel_hi:[1,0]
	v_pk_add_f32 v[78:79], v[110:111], 0 op_sel_hi:[1,0]
	v_pk_add_f32 v[46:47], v[46:47], 0 op_sel_hi:[1,0]
	v_lshlrev_b32_e32 v100, 16, v36
	v_and_b32_e32 v101, 0xffff0000, v36
	v_lshlrev_b32_e32 v36, 16, v37
	v_and_b32_e32 v37, 0xffff0000, v37
	v_lshlrev_b32_e32 v102, 16, v38
	v_and_b32_e32 v103, 0xffff0000, v38
	v_lshlrev_b32_e32 v38, 16, v39
	v_and_b32_e32 v39, 0xffff0000, v39
	v_pk_add_f32 v[82:83], v[82:83], 0 op_sel_hi:[1,0]
	v_lshlrev_b32_e32 v120, 16, v56
	v_and_b32_e32 v121, 0xffff0000, v56
	v_lshlrev_b32_e32 v56, 16, v57
	v_and_b32_e32 v57, 0xffff0000, v57
	v_lshlrev_b32_e32 v122, 16, v58
	v_and_b32_e32 v123, 0xffff0000, v58
	v_lshlrev_b32_e32 v58, 16, v59
	v_and_b32_e32 v59, 0xffff0000, v59
	v_lshlrev_b32_e32 v124, 16, v60
	v_and_b32_e32 v125, 0xffff0000, v60
	v_lshlrev_b32_e32 v60, 16, v61
	v_and_b32_e32 v61, 0xffff0000, v61
	v_lshlrev_b32_e32 v126, 16, v62
	v_and_b32_e32 v127, 0xffff0000, v62
	v_lshlrev_b32_e32 v62, 16, v63
	v_and_b32_e32 v63, 0xffff0000, v63
	v_pk_add_f32 v[24:25], v[80:81], v[88:89]
	v_pk_add_f32 v[80:81], v[112:113], 0 op_sel_hi:[1,0]
	v_pk_add_f32 v[48:49], v[48:49], 0 op_sel_hi:[1,0]
	v_pk_add_f32 v[50:51], v[50:51], 0 op_sel_hi:[1,0]
	v_pk_add_f32 v[20:21], v[20:21], v[92:93]
	v_pk_add_f32 v[12:13], v[12:13], v[28:29]
	v_pk_add_f32 v[22:23], v[22:23], v[94:95]
	v_pk_add_f32 v[14:15], v[14:15], v[30:31]
	v_pk_add_f32 v[16:17], v[16:17], v[32:33]
	v_pk_add_f32 v[18:19], v[18:19], v[34:35]
	v_pk_add_f32 v[28:29], v[44:45], v[52:53]
	v_pk_add_f32 v[30:31], v[76:77], v[116:117]
	v_pk_add_f32 v[32:33], v[46:47], v[54:55]
	v_pk_add_f32 v[34:35], v[78:79], v[118:119]
	v_lshlrev_b32_e32 v106, 16, v42
	v_and_b32_e32 v107, 0xffff0000, v42
	v_lshlrev_b32_e32 v42, 16, v43
	v_and_b32_e32 v43, 0xffff0000, v43
	v_lshlrev_b32_e32 v128, 16, v64
	v_and_b32_e32 v129, 0xffff0000, v64
	v_lshlrev_b32_e32 v64, 16, v65
	v_and_b32_e32 v65, 0xffff0000, v65
	v_lshlrev_b32_e32 v130, 16, v66
	v_and_b32_e32 v131, 0xffff0000, v66
	v_lshlrev_b32_e32 v66, 16, v67
	v_and_b32_e32 v67, 0xffff0000, v67
	v_lshlrev_b32_e32 v132, 16, v68
	v_and_b32_e32 v133, 0xffff0000, v68
	v_lshlrev_b32_e32 v68, 16, v69
	v_and_b32_e32 v69, 0xffff0000, v69
	v_lshlrev_b32_e32 v134, 16, v70
	v_and_b32_e32 v135, 0xffff0000, v70
	v_lshlrev_b32_e32 v70, 16, v71
	v_and_b32_e32 v71, 0xffff0000, v71
	v_pk_add_f32 v[26:27], v[82:83], v[90:91]
	v_pk_add_f32 v[82:83], v[114:115], 0 op_sel_hi:[1,0]
	v_pk_add_f32 v[44:45], v[48:49], v[56:57]
	v_pk_add_f32 v[46:47], v[80:81], v[120:121]
	v_pk_add_f32 v[48:49], v[50:51], v[58:59]
	v_pk_add_f32 v[12:13], v[12:13], v[36:37]
	v_pk_add_f32 v[20:21], v[20:21], v[100:101]
	v_pk_add_f32 v[14:15], v[14:15], v[38:39]
	v_pk_add_f32 v[22:23], v[22:23], v[102:103]
	v_pk_add_f32 v[30:31], v[30:31], v[124:125]
	v_pk_add_f32 v[28:29], v[28:29], v[60:61]
	v_pk_add_f32 v[34:35], v[34:35], v[126:127]
	v_pk_add_f32 v[32:33], v[32:33], v[62:63]
	v_lshlrev_b32_e32 v104, 16, v40
	v_and_b32_e32 v105, 0xffff0000, v40
	v_lshlrev_b32_e32 v40, 16, v41
	v_and_b32_e32 v41, 0xffff0000, v41
	v_pk_add_f32 v[50:51], v[82:83], v[122:123]
	v_pk_add_f32 v[18:19], v[18:19], v[42:43]
	v_pk_add_f32 v[36:37], v[46:47], v[128:129]
	v_pk_add_f32 v[38:39], v[44:45], v[64:65]
	v_pk_add_f32 v[42:43], v[48:49], v[66:67]
	v_pk_add_f32 v[28:29], v[28:29], v[68:69]
	v_pk_add_f32 v[30:31], v[30:31], v[132:133]
	v_pk_add_f32 v[32:33], v[32:33], v[70:71]
	v_pk_add_f32 v[34:35], v[34:35], v[134:135]
	v_mul_f32_e32 v2, 0xbfb8aa3b, v20
	v_mul_f32_e32 v11, 0xbfb8aa3b, v21
	v_pk_mul_f32 v[44:45], v[12:13], s[98:99]
	v_pk_mul_f32 v[46:47], v[22:23], s[98:99]
	v_pk_mul_f32 v[48:49], v[14:15], s[98:99]
	v_pk_add_f32 v[16:17], v[16:17], v[40:41]
	v_pk_add_f32 v[40:41], v[50:51], v[130:131]
	v_exp_f32_e32 v2, v2
	v_exp_f32_e32 v11, v11
	v_exp_f32_e32 v44, v44
	v_exp_f32_e32 v45, v45
	v_exp_f32_e32 v46, v46
	v_exp_f32_e32 v47, v47
	v_exp_f32_e32 v48, v48
	v_exp_f32_e32 v49, v49
	v_pk_mul_f32 v[50:51], v[30:31], s[98:99]
	v_pk_mul_f32 v[52:53], v[28:29], s[98:99]
	v_pk_mul_f32 v[54:55], v[34:35], s[98:99]
	v_pk_mul_f32 v[56:57], v[32:33], s[98:99]
	v_exp_f32_e32 v58, v50
	v_exp_f32_e32 v59, v51
	v_exp_f32_e32 v52, v52
	v_exp_f32_e32 v53, v53
	v_exp_f32_e32 v54, v54
	v_exp_f32_e32 v55, v55
	v_exp_f32_e32 v56, v56
	v_exp_f32_e32 v57, v57
	v_add_f32_e32 v2, 1.0, v2
	v_add_f32_e32 v11, 1.0, v11
	v_pk_add_f32 v[50:51], v[44:45], s[100:101]
	v_pk_add_f32 v[60:61], v[46:47], s[100:101]
	v_pk_add_f32 v[62:63], v[48:49], s[100:101]
	v_rcp_f32_e32 v44, v2
	v_rcp_f32_e32 v45, v11
	v_rcp_f32_e32 v46, v50
	v_rcp_f32_e32 v47, v51
	v_rcp_f32_e32 v48, v60
	v_rcp_f32_e32 v49, v61
	v_rcp_f32_e32 v50, v62
	v_rcp_f32_e32 v51, v63
	v_add_f32_e32 v2, 1.0, v58
	v_add_f32_e32 v11, 1.0, v59
	v_pk_add_f32 v[58:59], v[52:53], s[100:101]
	v_pk_add_f32 v[60:61], v[54:55], s[100:101]
	v_pk_add_f32 v[62:63], v[56:57], s[100:101]
	v_rcp_f32_e32 v52, v2
	v_rcp_f32_e32 v53, v11
	v_rcp_f32_e32 v54, v58
	v_rcp_f32_e32 v55, v59
	v_rcp_f32_e32 v56, v60
	v_rcp_f32_e32 v57, v61
	v_rcp_f32_e32 v58, v62
	v_rcp_f32_e32 v59, v63
	v_pk_add_f32 v[24:25], v[24:25], v[96:97]
	v_pk_add_f32 v[26:27], v[26:27], v[98:99]
	v_lshlrev_b32_e32 v136, 16, v72
	v_and_b32_e32 v137, 0xffff0000, v72
	v_lshlrev_b32_e32 v72, 16, v73
	v_and_b32_e32 v73, 0xffff0000, v73
	v_lshlrev_b32_e32 v138, 16, v74
	v_and_b32_e32 v139, 0xffff0000, v74
	v_lshlrev_b32_e32 v74, 16, v75
	v_and_b32_e32 v75, 0xffff0000, v75
	v_pk_add_f32 v[24:25], v[24:25], v[104:105]
	v_pk_add_f32 v[26:27], v[26:27], v[106:107]
	v_pk_mul_f32 v[20:21], v[20:21], v[44:45]
	v_pk_mul_f32 v[12:13], v[12:13], v[46:47]
	v_pk_mul_f32 v[22:23], v[22:23], v[48:49]
	v_pk_mul_f32 v[14:15], v[14:15], v[50:51]
	v_pk_add_f32 v[38:39], v[38:39], v[72:73]
	v_pk_add_f32 v[36:37], v[36:37], v[136:137]
	v_pk_add_f32 v[42:43], v[42:43], v[74:75]
	v_pk_add_f32 v[40:41], v[40:41], v[138:139]
	v_pk_mul_f32 v[20:21], v[24:25], v[20:21]
	v_pk_mul_f32 v[16:17], v[16:17], v[12:13]
	v_pk_mul_f32 v[22:23], v[26:27], v[22:23]
	v_pk_mul_f32 v[18:19], v[18:19], v[14:15]
	v_pk_mul_f32 v[24:25], v[30:31], v[52:53]
	v_pk_mul_f32 v[26:27], v[28:29], v[54:55]
	v_pk_mul_f32 v[28:29], v[34:35], v[56:57]
	v_pk_mul_f32 v[30:31], v[32:33], v[58:59]
	v_cvt_pk_bf16_f32 v12, v20, v21
	v_cvt_pk_bf16_f32 v13, v16, v17
	v_cvt_pk_bf16_f32 v14, v22, v23
	v_cvt_pk_bf16_f32 v15, v18, v19
	v_pk_mul_f32 v[16:17], v[36:37], v[24:25]
	v_pk_mul_f32 v[18:19], v[38:39], v[26:27]
	v_pk_mul_f32 v[20:21], v[40:41], v[28:29]
	v_pk_mul_f32 v[22:23], v[42:43], v[30:31]
	global_store_dwordx4 v[8:9], v[12:15], off
	s_nop 1
	v_cvt_pk_bf16_f32 v12, v16, v17
	v_cvt_pk_bf16_f32 v13, v18, v19
	v_cvt_pk_bf16_f32 v14, v20, v21
	v_cvt_pk_bf16_f32 v15, v22, v23
	global_store_dwordx4 v[6:7], v[12:15], off
	s_cbranch_scc1 .LBB0_1382

	.amdhsa_kernel _Z10fwd_kernel4Args
		.amdhsa_group_segment_fixed_size 0
		.amdhsa_private_segment_fixed_size 0
		.amdhsa_kernarg_size 504
		.amdhsa_user_sgpr_count 2
		.amdhsa_user_sgpr_dispatch_ptr 0
		.amdhsa_user_sgpr_queue_ptr 0
		.amdhsa_user_sgpr_kernarg_segment_ptr 1
		.amdhsa_user_sgpr_dispatch_id 0
		.amdhsa_user_sgpr_kernarg_preload_length 0
		.amdhsa_user_sgpr_kernarg_preload_offset 0
		.amdhsa_user_sgpr_private_segment_size 0
		.amdhsa_uses_dynamic_stack 0
		.amdhsa_enable_private_segment 0
		.amdhsa_system_sgpr_workgroup_id_x 1
		.amdhsa_system_sgpr_workgroup_id_y 0
		.amdhsa_system_sgpr_workgroup_id_z 0
		.amdhsa_system_sgpr_workgroup_info 0
		.amdhsa_system_vgpr_workitem_id 0
		.amdhsa_next_free_vgpr 250
		.amdhsa_next_free_sgpr 102
		.amdhsa_accum_offset 252
		.amdhsa_reserve_vcc 1
		.amdhsa_float_round_mode_32 0
		.amdhsa_float_round_mode_16_64 0
		.amdhsa_float_denorm_mode_32 3
		.amdhsa_float_denorm_mode_16_64 3
		.amdhsa_dx10_clamp 1
		.amdhsa_ieee_mode 1
		.amdhsa_fp16_overflow 0
		.amdhsa_tg_split 0
		.amdhsa_exception_fp_ieee_invalid_op 0
		.amdhsa_exception_fp_denorm_src 0
		.amdhsa_exception_fp_ieee_div_zero 0
		.amdhsa_exception_fp_ieee_overflow 0
		.amdhsa_exception_fp_ieee_underflow 0
		.amdhsa_exception_fp_ieee_inexact 0
		.amdhsa_exception_int_div_zero 0
	.end_amdhsa_kernel

amdhsa.kernels:
  - .agpr_count:     0
    .args:
      - .offset:         0
        .size:           248
        .value_kind:     by_value
      - .offset:         248
        .size:           4
        .value_kind:     hidden_block_count_x
      - .offset:         252
        .size:           4
        .value_kind:     hidden_block_count_y
      - .offset:         256
        .size:           4
        .value_kind:     hidden_block_count_z
      - .offset:         260
        .size:           2
        .value_kind:     hidden_group_size_x
      - .offset:         262
        .size:           2
        .value_kind:     hidden_group_size_y
      - .offset:         264
        .size:           2
        .value_kind:     hidden_group_size_z
      - .offset:         266
        .size:           2
        .value_kind:     hidden_remainder_x
      - .offset:         268
        .size:           2
        .value_kind:     hidden_remainder_y
      - .offset:         270
        .size:           2
        .value_kind:     hidden_remainder_z
      - .offset:         288
        .size:           8
        .value_kind:     hidden_global_offset_x
      - .offset:         296
        .size:           8
        .value_kind:     hidden_global_offset_y
      - .offset:         304
        .size:           8
        .value_kind:     hidden_global_offset_z
      - .offset:         312
        .size:           2
        .value_kind:     hidden_grid_dims
      - .offset:         368
        .size:           4
        .value_kind:     hidden_dynamic_lds_size
    .group_segment_fixed_size: 0
    .kernarg_segment_align: 8
    .kernarg_segment_size: 504
    .language:       OpenCL C
    .language_version:
      - 2
      - 0
    .max_flat_workgroup_size: 512
    .name:           _Z10fwd_kernel4Args
    .private_segment_fixed_size: 0
    .sgpr_count:     108
    .sgpr_spill_count: 138
    .symbol:         _Z10fwd_kernel4Args.kd
    .uniform_work_group_size: 1
    .uses_dynamic_stack: false
    .vgpr_count:     250
    .vgpr_spill_count: 0
    .wavefront_size: 64
